# baseline (speedup 1.0000x reference)
.LBB0_27:
	s_waitcnt vmcnt(0)
	v_mov_b32_e32 v0, v131
	s_mov_b32 s34, s83
	v_readlane_b32 s46, v255, 10
	s_cmpk_gt_i32 s46, 0x47f
	s_cbranch_scc1 .LBB0_44
	s_add_u32 s47, s26, 0x3c00000
	s_addc_u32 s86, s27, 0
	s_add_u32 s87, s26, 0x2d00000
	s_addc_u32 s73, s27, 0
	s_ashr_i32 s6, s46, 31
	s_lshr_b32 s6, s6, 29
	s_add_i32 s6, s46, s6
	s_ashr_i32 s7, s6, 3
	s_and_b32 s6, s6, -8
	s_sub_i32 s6, s46, s6
	s_cmp_lt_i32 s6, 0
	s_movk_i32 s8, 0x91
	s_cselect_b32 s8, s8, 0x90
	s_mul_i32 s6, s8, s6
	s_add_i32 s6, s6, s7
	s_mul_hi_i32 s7, s6, 0x38e38e39
	s_lshr_b32 s8, s7, 31
	s_ashr_i32 s7, s7, 4
	s_add_i32 s7, s7, s8
	s_mul_i32 s8, s7, 0x48
	s_sub_i32 s6, s6, s8
	s_bfe_i32 s8, s6, 0x80000
	s_bfe_u32 s8, s8, 0x3000c
	s_add_i32 s8, s6, s8
	s_bfe_i32 s9, s8, 0x80000
	s_and_b32 s8, s8, 0xf8
	s_sub_i32 s6, s6, s8
	s_sext_i32_i8 s6, s6
	v_ashrrev_i32_e32 v1, 6, v0
	v_lshrrev_b32_e32 v2, 31, v0
	s_sext_i32_i16 s9, s9
	s_lshl_b32 s7, s7, 11
	s_lshl_b32 s6, s6, 8
	v_add_u32_e32 v2, v1, v2
	v_lshlrev_b32_e32 v3, 9, v0
	s_add_i32 s38, s6, s7
	s_lshl_b32 s6, s9, 5
	s_waitcnt vmcnt(1)
	v_ashrrev_i32_e32 v8, 1, v2
	v_and_b32_e32 v9, 0x7800, v3
	v_and_b32_e32 v2, 0x3fffffe, v2
	s_and_b32 s22, s6, 0xffffff00
	v_lshl_or_b32 v3, v8, 15, v9
	v_sub_u32_e32 v2, v1, v2
	s_ashr_i32 s39, s38, 31
	s_ashr_i32 s23, s22, 31
	v_lshl_add_u32 v2, v2, 6, v3
	v_lshlrev_b32_e32 v3, 4, v0
	v_lshlrev_b32_e32 v142, 10, v1
	s_lshl_b64 s[6:7], s[38:39], 11
	s_lshl_b64 s[8:9], s[22:23], 11
	v_and_b32_e32 v10, 48, v3
	v_and_b32_e32 v11, 32, v0
	s_add_u32 s16, s87, s8
	v_add_u32_e32 v143, 0x10000, v142
	v_bitop3_b32 v128, v2, v10, v11 bitop3:0xf6
	s_addc_u32 s17, s73, s9
	v_readfirstlane_b32 s8, v143
	v_add_u32_e32 v144, 0x12000, v142
	v_lshl_add_u64 v[2:3], s[16:17], 0, v[128:129]
	s_mov_b32 m0, s8
	s_mov_b64 s[10:11], 0x20000
	v_readfirstlane_b32 s8, v144
	s_add_u32 s18, s47, s6
	global_load_lds_dwordx4 v128, s[16:17]
	v_lshl_add_u64 v[4:5], v[2:3], 0, s[10:11]
	s_mov_b32 m0, s8
	s_addc_u32 s19, s86, s7
	v_readfirstlane_b32 s6, v142
	v_add_u32_e32 v145, 0x2000, v142
	global_load_lds_dwordx4 v[4:5], off
	v_lshl_add_u64 v[4:5], s[18:19], 0, v[128:129]
	s_mov_b32 m0, s6
	v_readfirstlane_b32 s6, v145
	v_add_u32_e32 v146, 0x14000, v142
	global_load_lds_dwordx4 v128, s[18:19]
	v_lshl_add_u64 v[6:7], v[4:5], 0, s[10:11]
	s_mov_b32 m0, s6
	s_mov_b64 s[8:9], 0x40000
	v_readfirstlane_b32 s6, v146
	v_add_u32_e32 v147, 0x16000, v142
	global_load_lds_dwordx4 v[6:7], off
	v_lshl_add_u64 v[6:7], v[2:3], 0, s[8:9]
	s_mov_b32 m0, s6
	s_mov_b64 s[10:11], 0x60000
	v_readfirstlane_b32 s6, v147
	v_add_u32_e32 v148, 0x4000, v142
	global_load_lds_dwordx4 v[6:7], off
	v_lshl_add_u64 v[6:7], v[2:3], 0, s[10:11]
	s_mov_b32 m0, s6
	v_readfirstlane_b32 s6, v148
	v_add_u32_e32 v149, 0x6000, v142
	global_load_lds_dwordx4 v[6:7], off
	v_lshl_add_u64 v[6:7], v[4:5], 0, s[8:9]
	s_mov_b32 m0, s6
	v_readfirstlane_b32 s6, v149
	v_add_u32_e32 v150, 0x18000, v142
	global_load_lds_dwordx4 v[6:7], off
	v_lshl_add_u64 v[6:7], v[4:5], 0, s[10:11]
	s_mov_b32 m0, s6
	v_readfirstlane_b32 s6, v150
	v_add_u32_e32 v151, 0x1a000, v142
	global_load_lds_dwordx4 v[6:7], off
	v_lshl_add_u64 v[6:7], v[2:3], 0, s[44:45]
	s_mov_b32 m0, s6
	s_mov_b64 s[8:9], 0x20080
	v_readfirstlane_b32 s6, v151
	v_add_u32_e32 v152, 0x8000, v142
	global_load_lds_dwordx4 v[6:7], off
	v_lshl_add_u64 v[6:7], v[2:3], 0, s[8:9]
	s_mov_b32 m0, s6
	v_readfirstlane_b32 s6, v152
	v_add_u32_e32 v153, 0xa000, v142
	global_load_lds_dwordx4 v[6:7], off
	v_lshl_add_u64 v[6:7], v[4:5], 0, s[44:45]
	s_mov_b32 m0, s6
	v_readfirstlane_b32 s6, v153
	v_add_u32_e32 v154, 0x1c000, v142
	global_load_lds_dwordx4 v[6:7], off
	v_lshl_add_u64 v[4:5], v[4:5], 0, s[8:9]
	s_mov_b32 m0, s6
	v_readfirstlane_b32 s6, v154
	v_add_u32_e32 v155, 0x1e000, v142
	global_load_lds_dwordx4 v[4:5], off
	v_lshl_add_u64 v[4:5], v[2:3], 0, s[48:49]
	s_mov_b32 m0, s6
	v_readfirstlane_b32 s6, v155
	global_load_lds_dwordx4 v[4:5], off
	v_lshl_add_u64 v[2:3], v[2:3], 0, s[50:51]
	s_mov_b32 m0, s6
	s_load_dwordx2 s[12:13], s[0:1], 0xa8
	global_load_lds_dwordx4 v[2:3], off
	v_and_b32_e32 v2, 15, v0
	s_waitcnt vmcnt(0)
	v_lshlrev_b32_e32 v12, 2, v0
	v_ashrrev_i32_e32 v4, 8, v0
	v_and_b32_e32 v6, 48, v0
	v_lshlrev_b32_e32 v3, 6, v2
	v_and_b32_e32 v12, 32, v12
	v_or_b32_e32 v7, v3, v6
	v_bitop3_b32 v13, v3, v12, v6 bitop3:0x36
	v_lshlrev_b32_e32 v3, 6, v4
	v_lshrrev_b32_e32 v17, 2, v0
	s_mov_b32 s8, 0x10000
	v_and_or_b32 v157, v17, 12, v3
	v_lshlrev_b32_e32 v2, 2, v2
	v_mov_b32_e32 v3, v129
	v_bitop3_b32 v14, v7, s8, v12 bitop3:0xde
	s_mov_b32 s8, 0x14000
	s_waitcnt lgkmcnt(0)
	v_lshl_add_u64 v[252:253], s[12:13], 0, v[2:3]
	v_lshl_add_u64 v[2:3], s[26:27], 0, v[2:3]
	s_mov_b64 s[12:13], 0x7c00000
	v_and_b32_e32 v1, 3, v1
	v_bitop3_b32 v15, v7, s8, v12 bitop3:0xde
	s_mov_b32 s8, 0x18000
	v_lshl_add_u64 v[178:179], v[2:3], 0, s[12:13]
	v_and_b32_e32 v2, 14, v0
	v_bitop3_b32 v16, v7, s8, v12 bitop3:0xde
	s_mov_b32 s8, 0x1c000
	v_lshl_or_b32 v158, v1, 5, v2
	v_lshlrev_b32_e32 v2, 6, v0
	s_movk_i32 s23, 0x7f80
	v_lshlrev_b32_e32 v5, 12, v1
	v_bitop3_b32 v7, v7, s8, v12 bitop3:0xde
	s_movk_i32 s8, 0x100
	v_cmp_eq_u32_e64 s[10:11], 0, v1
	v_lshlrev_b32_e32 v1, 13, v4
	v_and_b32_e32 v2, 0x3c0, v2
	v_mul_lo_u32 v8, v8, s23
	v_cmp_eq_u32_e64 s[6:7], 1, v4
	v_cmp_gt_u32_e64 s[8:9], s8, v0
	v_and_b32_e32 v156, 1, v0
	v_bitop3_b32 v2, v2, v12, v6 bitop3:0x36
	v_or_b32_e32 v3, 0x800, v1
	v_or_b32_e32 v4, 0x1000, v1
	v_or_b32_e32 v6, 0x1800, v1
	v_bitop3_b32 v8, v10, v8, v11 bitop3:0xde
	v_and_b32_e32 v0, 0xffffffc0, v0
	v_cmp_eq_u32_e64 s[12:13], 0, v156
	v_add3_u32 v136, v8, v9, v0
	v_mov_b32_e32 v137, v129
	v_add_u32_e32 v159, v14, v5
	v_add_u32_e32 v160, v13, v1
	v_add_u32_e32 v161, v2, v3
	v_add_u32_e32 v162, v2, v4
	v_add_u32_e32 v163, v2, v6
	v_add_u32_e32 v164, 0xc000, v142
	v_add_u32_e32 v165, 0xe000, v142
	v_add_u32_e32 v166, v15, v5
	v_add_u32_e32 v167, v16, v5
	v_add_u32_e32 v168, v7, v5
	s_waitcnt vmcnt(0)
	s_branch .LBB0_30

.LBB0_30:
	v_mov_b64 v[0:1], 0
	v_mov_b64 v[2:3], 0
	v_mov_b64 v[4:5], 0
	v_mov_b64 v[6:7], 0
	v_mov_b64 v[8:9], 0
	v_mov_b64 v[10:11], 0
	v_mov_b64 v[12:13], 0
	v_mov_b64 v[14:15], 0
	v_mov_b64 v[16:17], 0
	v_mov_b64 v[18:19], 0
	v_mov_b64 v[20:21], 0
	v_mov_b64 v[22:23], 0
	v_mov_b64 v[24:25], 0
	v_mov_b64 v[26:27], 0
	v_mov_b64 v[28:29], 0
	v_mov_b64 v[30:31], 0
	v_mov_b64 v[32:33], 0
	v_mov_b64 v[34:35], 0
	v_mov_b64 v[36:37], 0
	v_mov_b64 v[38:39], 0
	v_mov_b64 v[40:41], 0
	v_mov_b64 v[42:43], 0
	v_mov_b64 v[44:45], 0
	v_mov_b64 v[46:47], 0
	v_mov_b64 v[48:49], 0
	v_mov_b64 v[50:51], 0
	v_mov_b64 v[52:53], 0
	v_mov_b64 v[54:55], 0
	v_mov_b64 v[56:57], 0
	v_mov_b64 v[58:59], 0
	v_mov_b64 v[60:61], 0
	v_mov_b64 v[62:63], 0
	v_mov_b64 v[64:65], 0
	v_mov_b64 v[66:67], 0
	v_mov_b64 v[68:69], 0
	v_mov_b64 v[70:71], 0
	v_mov_b64 v[72:73], 0
	v_mov_b64 v[74:75], 0
	v_mov_b64 v[76:77], 0
	v_mov_b64 v[78:79], 0
	v_mov_b64 v[80:81], 0
	v_mov_b64 v[82:83], 0
	v_mov_b64 v[84:85], 0
	v_mov_b64 v[86:87], 0
	v_mov_b64 v[88:89], 0
	v_mov_b64 v[90:91], 0
	v_mov_b64 v[92:93], 0
	v_mov_b64 v[94:95], 0
	v_mov_b64 v[96:97], 0
	v_mov_b64 v[98:99], 0
	v_mov_b64 v[100:101], 0
	v_mov_b64 v[102:103], 0
	v_mov_b64 v[104:105], 0
	v_mov_b64 v[106:107], 0
	v_mov_b64 v[108:109], 0
	v_mov_b64 v[110:111], 0
	v_mov_b64 v[112:113], 0
	v_mov_b64 v[114:115], 0
	v_mov_b64 v[116:117], 0
	v_mov_b64 v[118:119], 0
	v_mov_b64 v[120:121], 0
	v_mov_b64 v[122:123], 0
	v_mov_b64 v[124:125], 0
	v_mov_b64 v[126:127], 0
	s_and_saveexec_b64 s[36:37], s[6:7]
	s_cbranch_execz .LBB0_32
	s_barrier
.LBB0_32:
	s_or_b64 exec, exec, s[36:37]
	s_waitcnt vmcnt(63)
	s_mov_b32 s23, -2
	s_mov_b64 s[40:41], s[18:19]
	s_mov_b64 s[42:43], s[16:17]
	s_barrier
	s_barrier

.LBB0_42:
	s_or_b64 exec, exec, s[70:71]
	s_waitcnt vmcnt(0)
	s_cbranch_execnz .LBB0_29

.LBB0_71:
	s_add_u32 s43, s26, 0x3c00000
	v_readlane_b32 s14, v255, 20
	s_addc_u32 s46, s27, 0
	s_add_i32 s9, s14, -2
	v_readlane_b32 s15, v255, 21
	s_and_b64 s[6:7], s[6:7], exec
	s_cselect_b32 s6, s9, s14
	s_cselect_b32 s7, 0, s15
	s_mov_b32 s9, 0x1600000
	s_mul_i32 s7, s7, 0x580000
	s_mul_hi_u32 s11, s6, 0x580000
	s_cselect_b32 s9, s9, 0x2e00000
	s_add_i32 s11, s11, s7
	s_mul_i32 s6, s6, 0x580000
	s_add_u32 s6, s26, s6
	s_addc_u32 s7, s27, s11
	s_add_u32 s47, s6, s9
	s_addc_u32 s68, s7, 0
	s_add_i32 s6, s10, s8
	s_ashr_i32 s7, s6, 31
	s_lshr_b32 s7, s7, 27
	s_add_i32 s7, s6, s7
	s_and_b32 s8, s7, 0xffe0
	s_sub_i32 s6, s6, s8
	s_bfe_i32 s8, s6, 0x80000
	s_bfe_u32 s8, s8, 0x3000c
	s_add_i32 s8, s6, s8
	s_bfe_i32 s9, s8, 0x80000
	s_and_b32 s8, s8, 0xf8
	s_sub_i32 s6, s6, s8
	s_sext_i32_i8 s6, s6
	s_lshl_b32 s7, s7, 6
	s_sext_i32_i16 s9, s9
	s_and_b32 s7, s7, 0xfffff800
	s_lshl_b32 s6, s6, 8
	v_ashrrev_i32_e32 v1, 6, v0
	v_lshrrev_b32_e32 v4, 31, v0
	s_add_i32 s18, s6, s7
	s_ashr_i32 s6, s9, 3
	v_lshlrev_b32_e32 v2, 4, v0
	v_and_b32_e32 v3, 32, v0
	v_add_u32_e32 v4, v1, v4
	s_lshl_b32 s19, s6, 8
	s_mul_i32 s6, s6, 0xb0000
	v_lshlrev_b32_e32 v134, 10, v1
	v_ashrrev_i32_e32 v8, 1, v4
	v_bfe_u32 v9, v0, 2, 4
	v_and_b32_e32 v4, 0x3fffffe, v4
	v_bitop3_b32 v2, v2, v3, 48 bitop3:0x6c
	s_ashr_i32 s7, s6, 31
	v_lshl_or_b32 v5, v8, 4, v9
	v_sub_u32_e32 v4, v1, v4
	v_lshrrev_b32_e32 v10, 1, v2
	s_movk_i32 s37, 0xb00
	s_lshl_b64 s[6:7], s[6:7], 1
	v_add_u32_e32 v135, 0x10000, v134
	v_lshl_or_b32 v2, v4, 5, v10
	v_mul_lo_u32 v3, v5, s37
	s_add_u32 s14, s47, s6
	v_readfirstlane_b32 s6, v135
	v_add_u32_e32 v136, 0x12000, v134
	v_add_lshl_u32 v128, v2, v3, 1
	s_addc_u32 s15, s68, s7
	s_mov_b32 m0, s6
	v_readfirstlane_b32 s6, v136
	s_mul_i32 s7, s18, 0x1600
	v_lshl_add_u64 v[2:3], s[14:15], 0, v[128:129]
	global_load_lds_dwordx4 v128, s[14:15]
	s_mov_b64 s[8:9], 0x58000
	s_mov_b32 m0, s6
	s_mul_hi_i32 s6, s18, 0x1600
	s_add_u32 s22, s43, s7
	v_lshl_add_u64 v[4:5], v[2:3], 0, s[8:9]
	s_addc_u32 s23, s46, s6
	v_readfirstlane_b32 s6, v134
	v_add_u32_e32 v137, 0x2000, v134
	global_load_lds_dwordx4 v[4:5], off
	v_lshl_add_u64 v[4:5], s[22:23], 0, v[128:129]
	s_mov_b32 m0, s6
	v_readfirstlane_b32 s6, v137
	v_add_u32_e32 v138, 0x14000, v134
	global_load_lds_dwordx4 v128, s[22:23]
	v_lshl_add_u64 v[6:7], v[4:5], 0, s[8:9]
	s_mov_b32 m0, s6
	s_mov_b64 s[8:9], 0xb0000
	v_readfirstlane_b32 s6, v138
	v_add_u32_e32 v139, 0x16000, v134
	global_load_lds_dwordx4 v[6:7], off
	v_lshl_add_u64 v[6:7], v[2:3], 0, s[8:9]
	s_mov_b32 m0, s6
	s_mov_b64 s[10:11], 0x108000
	v_readfirstlane_b32 s6, v139
	v_add_u32_e32 v140, 0x4000, v134
	global_load_lds_dwordx4 v[6:7], off
	v_lshl_add_u64 v[6:7], v[2:3], 0, s[10:11]
	s_mov_b32 m0, s6
	v_readfirstlane_b32 s6, v140
	v_add_u32_e32 v141, 0x6000, v134
	global_load_lds_dwordx4 v[6:7], off
	v_lshl_add_u64 v[6:7], v[4:5], 0, s[8:9]
	s_mov_b32 m0, s6
	v_readfirstlane_b32 s6, v141
	v_add_u32_e32 v142, 0x18000, v134
	global_load_lds_dwordx4 v[6:7], off
	v_lshl_add_u64 v[6:7], v[4:5], 0, s[10:11]
	s_mov_b32 m0, s6
	v_readfirstlane_b32 s6, v142
	v_add_u32_e32 v143, 0x1a000, v134
	global_load_lds_dwordx4 v[6:7], off
	v_lshl_add_u64 v[6:7], v[2:3], 0, s[44:45]
	s_mov_b32 m0, s6
	s_mov_b64 s[8:9], 0x58080
	v_readfirstlane_b32 s6, v143
	v_add_u32_e32 v144, 0x8000, v134
	global_load_lds_dwordx4 v[6:7], off
	v_lshl_add_u64 v[6:7], v[2:3], 0, s[8:9]
	s_mov_b32 m0, s6
	v_readfirstlane_b32 s6, v144
	v_add_u32_e32 v145, 0xa000, v134
	global_load_lds_dwordx4 v[6:7], off
	v_lshl_add_u64 v[6:7], v[4:5], 0, s[44:45]
	s_mov_b32 m0, s6
	v_readfirstlane_b32 s6, v145
	global_load_lds_dwordx4 v[6:7], off
	v_lshl_add_u64 v[4:5], v[4:5], 0, s[8:9]
	s_mov_b32 m0, s6
	s_mov_b64 s[6:7], 0xb0080
	v_add_u32_e32 v146, 0x1c000, v134
	global_load_lds_dwordx4 v[4:5], off
	v_lshl_add_u64 v[4:5], v[2:3], 0, s[6:7]
	v_readfirstlane_b32 s6, v146
	s_mov_b32 m0, s6
	s_mov_b64 s[6:7], 0x108080
	v_add_u32_e32 v147, 0x1e000, v134
	v_lshl_add_u64 v[2:3], v[2:3], 0, s[6:7]
	v_readfirstlane_b32 s6, v147
	global_load_lds_dwordx4 v[4:5], off
	s_mov_b32 m0, s6
	v_and_b32_e32 v4, 15, v0
	global_load_lds_dwordx4 v[2:3], off
	v_and_b32_e32 v7, 48, v0
	v_lshlrev_b32_e32 v4, 6, v4
	v_lshlrev_b32_e32 v12, 2, v0
	v_or_b32_e32 v11, v4, v7
	v_and_b32_e32 v12, 32, v12
	s_mov_b32 s8, 0x10000
	v_bitop3_b32 v13, v11, s8, v12 bitop3:0xde
	s_mov_b32 s8, 0x14000
	v_bitop3_b32 v15, v11, s8, v12 bitop3:0xde
	s_mov_b32 s8, 0x18000
	v_ashrrev_i32_e32 v2, 8, v0
	v_lshrrev_b32_e32 v5, 2, v0
	v_bitop3_b32 v16, v11, s8, v12 bitop3:0xde
	s_mov_b32 s8, 0x1c000
	v_lshlrev_b32_e32 v14, 6, v2
	v_bitop3_b32 v11, v11, s8, v12 bitop3:0xde
	s_movk_i32 s8, 0x100
	v_and_b32_e32 v17, 1, v0
	v_and_b32_e32 v5, 12, v5
	s_mov_b32 s36, 0xafc0
	v_cmp_gt_u32_e64 s[8:9], s8, v0
	v_or3_b32 v148, v14, v5, v17
	v_and_b32_e32 v5, 14, v0
	v_lshlrev_b32_e32 v0, 6, v0
	v_mul_lo_u32 v8, v8, s36
	v_and_b32_e32 v3, 3, v1
	v_cmp_eq_u32_e64 s[6:7], 1, v2
	v_lshlrev_b32_e32 v2, 13, v2
	v_and_b32_e32 v0, 0x3c0, v0
	v_or_b32_e32 v8, v10, v8
	v_lshlrev_b32_e32 v6, 12, v3
	v_bitop3_b32 v4, v4, v12, v7 bitop3:0x36
	v_lshl_or_b32 v149, v3, 5, v5
	v_bitop3_b32 v0, v0, v12, v7 bitop3:0x36
	v_or_b32_e32 v3, 0x800, v2
	v_or_b32_e32 v5, 0x1000, v2
	v_or_b32_e32 v7, 0x1800, v2
	v_mad_u32_u24 v8, v9, s37, v8
	v_lshlrev_b32_e32 v1, 5, v1
	v_cmp_eq_u32_e64 s[10:11], 0, v17
	v_add_lshl_u32 v132, v8, v1, 1
	v_mov_b32_e32 v133, v129
	v_add_u32_e32 v150, v13, v6
	v_add_u32_e32 v151, v4, v2
	v_add_u32_e32 v152, v0, v3
	v_add_u32_e32 v153, v0, v5
	v_add_u32_e32 v154, v0, v7
	v_add_u32_e32 v155, v15, v6
	v_add_u32_e32 v156, v16, v6
	v_add_u32_e32 v157, v11, v6
	s_waitcnt vmcnt(0)
	s_branch .LBB0_74

.LBB0_76:
	s_or_b64 exec, exec, s[36:37]
	s_waitcnt vmcnt(63)
	s_mov_b32 s36, -2
	s_mov_b64 s[38:39], s[22:23]
	s_mov_b64 s[40:41], s[14:15]
	s_mov_b64 s[76:77], 0xb0080
	s_mov_b64 s[78:79], 0x108080
	s_barrier
	s_barrier

.LBB0_93:
	s_waitcnt vmcnt(0)
	v_mov_b32_e32 v0, v131
	s_mov_b32 s34, s83
	s_mov_b32 s36, s73
	s_cmpk_gt_i32 s36, 0xaff
	s_cbranch_scc1 .LBB0_104
	s_add_u32 s37, s26, s6
	s_addc_u32 s46, s27, s7
	s_add_u32 s14, s26, 0x3c00000
	s_addc_u32 s15, s27, 0
	s_ashr_i32 s6, s36, 31
	s_lshr_b32 s6, s6, 29
	s_add_i32 s6, s36, s6
	s_ashr_i32 s7, s6, 3
	s_and_b32 s6, s6, -8
	s_sub_i32 s6, s36, s6
	s_cmp_lt_i32 s6, 0
	s_movk_i32 s8, 0x161
	s_cselect_b32 s8, s8, 0x160
	s_mul_i32 s6, s8, s6
	s_add_i32 s6, s6, s7
	s_mul_hi_i32 s7, s6, 0x2e8ba2e9
	s_lshr_b32 s8, s7, 31
	s_ashr_i32 s7, s7, 5
	s_add_i32 s7, s7, s8
	s_mul_i32 s8, s7, 0xb0
	s_sub_i32 s6, s6, s8
	s_bfe_u32 s8, s6, 0x3001c
	s_add_i32 s8, s6, s8
	s_sext_i32_i16 s9, s8
	s_and_b32 s8, s8, 0xfff8
	s_sub_i32 s6, s6, s8
	s_sext_i32_i16 s6, s6
	v_ashrrev_i32_e32 v1, 6, v0
	v_lshrrev_b32_e32 v2, 31, v0
	s_lshl_b32 s7, s7, 11
	s_lshl_b32 s6, s6, 8
	v_add_u32_e32 v2, v1, v2
	v_lshlrev_b32_e32 v3, 9, v0
	s_add_i32 s76, s6, s7
	s_lshl_b32 s6, s9, 5
	v_ashrrev_i32_e32 v8, 1, v2
	v_and_b32_e32 v9, 0x7800, v3
	v_and_b32_e32 v2, 0x3fffffe, v2
	s_and_b32 s78, s6, 0xffffff00
	v_lshl_or_b32 v3, v8, 15, v9
	v_sub_u32_e32 v2, v1, v2
	s_ashr_i32 s77, s76, 31
	s_ashr_i32 s79, s78, 31
	v_lshl_add_u32 v2, v2, 6, v3
	v_lshlrev_b32_e32 v3, 4, v0
	v_lshlrev_b32_e32 v134, 10, v1
	s_lshl_b64 s[6:7], s[76:77], 11
	s_lshl_b64 s[8:9], s[78:79], 11
	v_and_b32_e32 v10, 48, v3
	v_and_b32_e32 v11, 32, v0
	s_add_u32 s68, s37, s8
	v_add_u32_e32 v135, 0x10000, v134
	v_bitop3_b32 v128, v2, v10, v11 bitop3:0xf6
	s_addc_u32 s69, s46, s9
	v_readfirstlane_b32 s8, v135
	v_add_u32_e32 v136, 0x12000, v134
	v_lshl_add_u64 v[2:3], s[68:69], 0, v[128:129]
	s_mov_b32 m0, s8
	s_mov_b64 s[10:11], 0x20000
	v_readfirstlane_b32 s8, v136
	s_add_u32 s70, s16, s6
	global_load_lds_dwordx4 v128, s[68:69]
	v_lshl_add_u64 v[4:5], v[2:3], 0, s[10:11]
	s_mov_b32 m0, s8
	s_addc_u32 s71, s17, s7
	v_readfirstlane_b32 s6, v134
	v_add_u32_e32 v137, 0x2000, v134
	global_load_lds_dwordx4 v[4:5], off
	v_lshl_add_u64 v[4:5], s[70:71], 0, v[128:129]
	s_mov_b32 m0, s6
	v_readfirstlane_b32 s6, v137
	v_add_u32_e32 v138, 0x14000, v134
	global_load_lds_dwordx4 v128, s[70:71]
	v_lshl_add_u64 v[6:7], v[4:5], 0, s[10:11]
	s_mov_b32 m0, s6
	s_mov_b64 s[8:9], 0x40000
	v_readfirstlane_b32 s6, v138
	v_add_u32_e32 v139, 0x16000, v134
	global_load_lds_dwordx4 v[6:7], off
	v_lshl_add_u64 v[6:7], v[2:3], 0, s[8:9]
	s_mov_b32 m0, s6
	s_mov_b64 s[10:11], 0x60000
	v_readfirstlane_b32 s6, v139
	v_add_u32_e32 v140, 0x4000, v134
	global_load_lds_dwordx4 v[6:7], off
	v_lshl_add_u64 v[6:7], v[2:3], 0, s[10:11]
	s_mov_b32 m0, s6
	v_readfirstlane_b32 s6, v140
	v_add_u32_e32 v141, 0x6000, v134
	global_load_lds_dwordx4 v[6:7], off
	v_lshl_add_u64 v[6:7], v[4:5], 0, s[8:9]
	s_mov_b32 m0, s6
	v_readfirstlane_b32 s6, v141
	v_add_u32_e32 v142, 0x18000, v134
	global_load_lds_dwordx4 v[6:7], off
	v_lshl_add_u64 v[6:7], v[4:5], 0, s[10:11]
	s_mov_b32 m0, s6
	v_readfirstlane_b32 s6, v142
	v_add_u32_e32 v143, 0x1a000, v134
	global_load_lds_dwordx4 v[6:7], off
	v_lshl_add_u64 v[6:7], v[2:3], 0, s[44:45]
	s_mov_b32 m0, s6
	s_mov_b64 s[8:9], 0x20080
	v_readfirstlane_b32 s6, v143
	v_add_u32_e32 v144, 0x8000, v134
	global_load_lds_dwordx4 v[6:7], off
	v_lshl_add_u64 v[6:7], v[2:3], 0, s[8:9]
	s_mov_b32 m0, s6
	v_readfirstlane_b32 s6, v144
	v_add_u32_e32 v145, 0xa000, v134
	global_load_lds_dwordx4 v[6:7], off
	v_lshl_add_u64 v[6:7], v[4:5], 0, s[44:45]
	s_mov_b32 m0, s6
	v_readfirstlane_b32 s6, v145
	v_add_u32_e32 v146, 0x1c000, v134
	global_load_lds_dwordx4 v[6:7], off
	v_lshl_add_u64 v[4:5], v[4:5], 0, s[8:9]
	s_mov_b32 m0, s6
	v_readfirstlane_b32 s6, v146
	v_add_u32_e32 v147, 0x1e000, v134
	global_load_lds_dwordx4 v[4:5], off
	v_lshl_add_u64 v[4:5], v[2:3], 0, s[48:49]
	s_mov_b32 m0, s6
	v_readfirstlane_b32 s6, v147
	global_load_lds_dwordx4 v[4:5], off
	v_lshl_add_u64 v[2:3], v[2:3], 0, s[50:51]
	s_mov_b32 m0, s6
	v_and_b32_e32 v5, 48, v0
	global_load_lds_dwordx4 v[2:3], off
	v_and_b32_e32 v2, 15, v0
	v_lshlrev_b32_e32 v2, 6, v2
	v_lshlrev_b32_e32 v7, 2, v0
	v_ashrrev_i32_e32 v3, 8, v0
	v_or_b32_e32 v6, v2, v5
	v_and_b32_e32 v7, 32, v7
	s_mov_b32 s8, 0x10000
	v_lshrrev_b32_e32 v17, 2, v0
	v_bitop3_b32 v12, v6, s8, v7 bitop3:0xde
	v_lshlrev_b32_e32 v13, 6, v3
	s_mov_b32 s8, 0x14000
	v_and_b32_e32 v16, 1, v0
	v_and_b32_e32 v17, 12, v17
	v_and_b32_e32 v1, 3, v1
	v_bitop3_b32 v14, v6, s8, v7 bitop3:0xde
	s_mov_b32 s8, 0x18000
	v_or3_b32 v148, v13, v17, v16
	v_and_b32_e32 v13, 14, v0
	v_cmp_eq_u32_e64 s[6:7], 1, v3
	v_lshlrev_b32_e32 v4, 12, v1
	v_bitop3_b32 v15, v6, s8, v7 bitop3:0xde
	s_mov_b32 s8, 0x1c000
	v_lshl_or_b32 v149, v1, 5, v13
	v_lshlrev_b32_e32 v1, 13, v3
	v_lshlrev_b32_e32 v3, 6, v0
	s_movk_i32 s18, 0x7f80
	v_bitop3_b32 v6, v6, s8, v7 bitop3:0xde
	s_movk_i32 s8, 0x100
	v_and_b32_e32 v3, 0x3c0, v3
	v_mul_lo_u32 v8, v8, s18
	v_bitop3_b32 v2, v2, v7, v5 bitop3:0x36
	v_cmp_gt_u32_e64 s[8:9], s8, v0
	v_bitop3_b32 v3, v3, v7, v5 bitop3:0x36
	v_or_b32_e32 v5, 0x800, v1
	v_or_b32_e32 v7, 0x1000, v1
	v_or_b32_e32 v13, 0x1800, v1
	v_bitop3_b32 v8, v10, v8, v11 bitop3:0xde
	v_and_b32_e32 v0, 0xffffffc0, v0
	v_cmp_eq_u32_e64 s[10:11], 0, v16
	v_add3_u32 v132, v8, v9, v0
	v_mov_b32_e32 v133, v129
	v_add_u32_e32 v150, v12, v4
	v_add_u32_e32 v151, v2, v1
	v_add_u32_e32 v152, v3, v5
	v_add_u32_e32 v153, v3, v7
	v_add_u32_e32 v154, v3, v13
	v_add_u32_e32 v155, v14, v4
	v_add_u32_e32 v156, v15, v4
	v_add_u32_e32 v157, v6, v4
	s_waitcnt vmcnt(0)
	s_branch .LBB0_96

.LBB0_96:
	v_mov_b64 v[0:1], 0
	v_mov_b64 v[2:3], 0
	v_mov_b64 v[4:5], 0
	v_mov_b64 v[6:7], 0
	v_mov_b64 v[8:9], 0
	v_mov_b64 v[10:11], 0
	v_mov_b64 v[12:13], 0
	v_mov_b64 v[14:15], 0
	v_mov_b64 v[16:17], 0
	v_mov_b64 v[18:19], 0
	v_mov_b64 v[20:21], 0
	v_mov_b64 v[22:23], 0
	v_mov_b64 v[24:25], 0
	v_mov_b64 v[26:27], 0
	v_mov_b64 v[28:29], 0
	v_mov_b64 v[30:31], 0
	v_mov_b64 v[32:33], 0
	v_mov_b64 v[34:35], 0
	v_mov_b64 v[36:37], 0
	v_mov_b64 v[38:39], 0
	v_mov_b64 v[40:41], 0
	v_mov_b64 v[42:43], 0
	v_mov_b64 v[44:45], 0
	v_mov_b64 v[46:47], 0
	v_mov_b64 v[48:49], 0
	v_mov_b64 v[50:51], 0
	v_mov_b64 v[52:53], 0
	v_mov_b64 v[54:55], 0
	v_mov_b64 v[56:57], 0
	v_mov_b64 v[58:59], 0
	v_mov_b64 v[60:61], 0
	v_mov_b64 v[62:63], 0
	v_mov_b64 v[64:65], 0
	v_mov_b64 v[66:67], 0
	v_mov_b64 v[68:69], 0
	v_mov_b64 v[70:71], 0
	v_mov_b64 v[72:73], 0
	v_mov_b64 v[74:75], 0
	v_mov_b64 v[76:77], 0
	v_mov_b64 v[78:79], 0
	v_mov_b64 v[80:81], 0
	v_mov_b64 v[82:83], 0
	v_mov_b64 v[84:85], 0
	v_mov_b64 v[86:87], 0
	v_mov_b64 v[88:89], 0
	v_mov_b64 v[90:91], 0
	v_mov_b64 v[92:93], 0
	v_mov_b64 v[94:95], 0
	v_mov_b64 v[96:97], 0
	v_mov_b64 v[98:99], 0
	v_mov_b64 v[100:101], 0
	v_mov_b64 v[102:103], 0
	v_mov_b64 v[104:105], 0
	v_mov_b64 v[106:107], 0
	v_mov_b64 v[108:109], 0
	v_mov_b64 v[110:111], 0
	v_mov_b64 v[112:113], 0
	v_mov_b64 v[114:115], 0
	v_mov_b64 v[116:117], 0
	v_mov_b64 v[118:119], 0
	v_mov_b64 v[120:121], 0
	v_mov_b64 v[122:123], 0
	v_mov_b64 v[124:125], 0
	v_mov_b64 v[126:127], 0
	s_and_saveexec_b64 s[22:23], s[6:7]
	s_cbranch_execz .LBB0_98
	s_barrier
.LBB0_98:
	s_or_b64 exec, exec, s[22:23]
	s_waitcnt vmcnt(32)
	s_mov_b32 s18, -2
	s_mov_b64 s[22:23], s[70:71]
	s_mov_b64 s[38:39], s[68:69]
	s_barrier
	s_barrier

.LBB0_129:
	s_ashr_i32 s6, s9, 3
	s_add_i32 s6, s8, s6
	s_ashr_i32 s7, s6, 31
	s_lshr_b32 s7, s7, 27
	s_add_i32 s7, s6, s7
	s_and_b32 s8, s7, 0xffe0
	s_sub_i32 s6, s6, s8
	s_bfe_i32 s8, s6, 0x80000
	s_bfe_u32 s8, s8, 0x3000c
	s_add_i32 s8, s6, s8
	s_bfe_i32 s9, s8, 0x80000
	s_and_b32 s8, s8, 0xf8
	s_sub_i32 s6, s6, s8
	s_sext_i32_i8 s6, s6
	s_lshl_b32 s7, s7, 6
	s_sext_i32_i16 s9, s9
	s_and_b32 s7, s7, 0xfffff800
	s_lshl_b32 s6, s6, 8
	v_ashrrev_i32_e32 v1, 6, v0
	v_lshrrev_b32_e32 v4, 31, v0
	s_add_i32 s19, s6, s7
	s_lshl_b32 s6, s9, 5
	v_lshlrev_b32_e32 v2, 4, v0
	v_and_b32_e32 v3, 32, v0
	v_add_u32_e32 v4, v1, v4
	s_and_b32 s80, s6, 0xffffff00
	v_ashrrev_i32_e32 v16, 1, v4
	v_bfe_u32 v5, v0, 2, 4
	v_and_b32_e32 v4, 0x3fffffe, v4
	v_bitop3_b32 v2, v2, v3, 48 bitop3:0x6c
	s_mul_hi_i32 s9, s80, s36
	s_mul_i32 s8, s80, s36
	v_lshlrev_b32_e32 v134, 10, v1
	v_lshl_or_b32 v5, v16, 4, v5
	v_sub_u32_e32 v4, v1, v4
	v_lshrrev_b32_e32 v17, 1, v2
	s_lshr_b32 s10, s36, 6
	s_lshl_b64 s[8:9], s[8:9], 1
	v_lshl_or_b32 v2, v4, 5, v17
	v_mul_lo_u32 v18, v5, s36
	s_mul_hi_i32 s7, s19, s36
	s_mul_i32 s6, s19, s36
	s_waitcnt lgkmcnt(0)
	s_add_u32 s14, s2, s8
	v_add_u32_e32 v135, 0x10000, v134
	v_add_lshl_u32 v128, v2, v18, 1
	s_addc_u32 s15, s3, s9
	s_lshl_b32 s34, s36, 7
	v_readfirstlane_b32 s8, v135
	v_add_u32_e32 v136, 0x12000, v134
	s_lshl_b64 s[6:7], s[6:7], 1
	v_lshl_add_u64 v[2:3], s[14:15], 0, v[128:129]
	s_mov_b32 m0, s8
	v_readfirstlane_b32 s8, v136
	s_add_u32 s38, s16, s6
	global_load_lds_dwordx4 v128, s[14:15]
	v_lshl_add_u64 v[4:5], v[2:3], 0, s[34:35]
	s_mov_b32 m0, s8
	s_addc_u32 s39, s17, s7
	v_readfirstlane_b32 s6, v134
	v_add_u32_e32 v137, 0x2000, v134
	global_load_lds_dwordx4 v[4:5], off
	v_lshl_add_u64 v[6:7], s[38:39], 0, v[128:129]
	s_mov_b32 m0, s6
	v_readfirstlane_b32 s6, v137
	s_lshl_b32 s86, s36, 8
	v_add_u32_e32 v138, 0x14000, v134
	global_load_lds_dwordx4 v128, s[38:39]
	v_lshl_add_u64 v[8:9], v[6:7], 0, s[34:35]
	s_mov_b32 m0, s6
	s_add_u32 s6, s14, s86
	v_readfirstlane_b32 s8, v138
	global_load_lds_dwordx4 v[8:9], off
	s_addc_u32 s7, s15, 0
	s_mov_b32 m0, s8
	v_add_u32_e32 v139, 0x16000, v134
	v_lshl_add_u64 v[10:11], s[6:7], 0, v[128:129]
	global_load_lds_dwordx4 v128, s[6:7]
	v_readfirstlane_b32 s6, v139
	v_add_u32_e32 v140, 0x4000, v134
	v_lshl_add_u64 v[12:13], v[10:11], 0, s[34:35]
	s_mov_b32 m0, s6
	s_add_u32 s6, s38, s86
	v_readfirstlane_b32 s8, v140
	global_load_lds_dwordx4 v[12:13], off
	s_addc_u32 s7, s39, 0
	s_mov_b32 m0, s8
	v_add_u32_e32 v141, 0x6000, v134
	v_lshl_add_u64 v[14:15], s[6:7], 0, v[128:129]
	global_load_lds_dwordx4 v128, s[6:7]
	v_readfirstlane_b32 s6, v141
	v_add_u32_e32 v142, 0x18000, v134
	v_lshl_add_u64 v[14:15], v[14:15], 0, s[34:35]
	s_mov_b32 m0, s6
	v_readfirstlane_b32 s6, v142
	v_add_u32_e32 v143, 0x1a000, v134
	global_load_lds_dwordx4 v[14:15], off
	v_lshl_add_u64 v[2:3], v[2:3], 0, s[44:45]
	s_mov_b32 m0, s6
	v_readfirstlane_b32 s6, v143
	v_add_u32_e32 v144, 0x8000, v134
	global_load_lds_dwordx4 v[2:3], off
	v_lshl_add_u64 v[2:3], v[4:5], 0, s[44:45]
	s_mov_b32 m0, s6
	v_readfirstlane_b32 s6, v144
	v_add_u32_e32 v145, 0xa000, v134
	global_load_lds_dwordx4 v[2:3], off
	v_lshl_add_u64 v[2:3], v[6:7], 0, s[44:45]
	s_mov_b32 m0, s6
	v_readfirstlane_b32 s6, v145
	v_add_u32_e32 v146, 0x1c000, v134
	global_load_lds_dwordx4 v[2:3], off
	v_lshl_add_u64 v[2:3], v[8:9], 0, s[44:45]
	s_mov_b32 m0, s6
	v_readfirstlane_b32 s6, v146
	v_add_u32_e32 v147, 0x1e000, v134
	global_load_lds_dwordx4 v[2:3], off
	v_lshl_add_u64 v[2:3], v[10:11], 0, s[44:45]
	s_mov_b32 m0, s6
	v_readfirstlane_b32 s6, v147
	global_load_lds_dwordx4 v[2:3], off
	v_lshl_add_u64 v[2:3], v[12:13], 0, s[44:45]
	s_mov_b32 m0, s6
	v_and_b32_e32 v4, 15, v0
	global_load_lds_dwordx4 v[2:3], off
	v_and_b32_e32 v7, 48, v0
	v_lshlrev_b32_e32 v4, 6, v4
	v_lshlrev_b32_e32 v9, 2, v0
	v_or_b32_e32 v8, v4, v7
	v_and_b32_e32 v9, 32, v9
	s_mov_b32 s8, 0x10000
	v_bitop3_b32 v10, v8, s8, v9 bitop3:0xde
	s_mov_b32 s8, 0x14000
	v_bitop3_b32 v12, v8, s8, v9 bitop3:0xde
	s_mov_b32 s8, 0x18000
	v_bitop3_b32 v13, v8, s8, v9 bitop3:0xde
	s_mov_b32 s8, 0x1c000
	v_ashrrev_i32_e32 v2, 8, v0
	v_lshrrev_b32_e32 v5, 2, v0
	v_bitop3_b32 v8, v8, s8, v9 bitop3:0xde
	s_add_i32 s8, s10, -1
	s_mov_b32 s9, s35
	v_lshlrev_b32_e32 v11, 6, v2
	s_lshl_b64 s[40:41], s[8:9], 7
	s_movk_i32 s8, 0x100
	v_and_b32_e32 v14, 1, v0
	v_and_b32_e32 v5, 12, v5
	v_cmp_gt_u32_e64 s[8:9], s8, v0
	v_or3_b32 v148, v11, v5, v14
	v_and_b32_e32 v5, 14, v0
	v_lshlrev_b32_e32 v0, 6, v0
	v_and_b32_e32 v3, 3, v1
	v_and_b32_e32 v0, 0x3c0, v0
	v_lshlrev_b32_e32 v1, 5, v1
	v_cmp_eq_u32_e64 s[6:7], 1, v2
	v_bitop3_b32 v4, v4, v9, v7 bitop3:0x36
	v_lshlrev_b32_e32 v2, 13, v2
	v_bitop3_b32 v0, v0, v9, v7 bitop3:0x36
	v_add3_u32 v1, v17, v18, v1
	v_lshlrev_b32_e32 v9, 6, v16
	v_lshlrev_b32_e32 v6, 12, v3
	v_lshl_or_b32 v149, v3, 5, v5
	v_or_b32_e32 v3, 0x800, v2
	v_or_b32_e32 v5, 0x1000, v2
	v_or_b32_e32 v7, 0x1800, v2
	v_sub_u32_e32 v1, v1, v9
	s_add_i32 s87, s10, -2
	v_cmp_eq_u32_e64 s[10:11], 0, v14
	v_lshlrev_b32_e32 v132, 1, v1
	v_mov_b32_e32 v133, v129
	s_mul_i32 s18, s36, 0x180
	v_add_u32_e32 v150, v10, v6
	v_add_u32_e32 v151, v4, v2
	v_add_u32_e32 v152, v0, v3
	v_add_u32_e32 v153, v0, v5
	v_add_u32_e32 v154, v0, v7
	v_add_u32_e32 v155, v12, v6
	v_add_u32_e32 v156, v13, v6
	v_add_u32_e32 v157, v8, v6
	s_waitcnt vmcnt(0)
	s_branch .LBB0_132

.LBB0_132:
	v_mov_b64 v[0:1], 0
	v_mov_b64 v[2:3], 0
	v_mov_b64 v[4:5], 0
	v_mov_b64 v[6:7], 0
	v_mov_b64 v[8:9], 0
	v_mov_b64 v[10:11], 0
	v_mov_b64 v[12:13], 0
	v_mov_b64 v[14:15], 0
	v_mov_b64 v[16:17], 0
	v_mov_b64 v[18:19], 0
	v_mov_b64 v[20:21], 0
	v_mov_b64 v[22:23], 0
	v_mov_b64 v[24:25], 0
	v_mov_b64 v[26:27], 0
	v_mov_b64 v[28:29], 0
	v_mov_b64 v[30:31], 0
	v_mov_b64 v[32:33], 0
	v_mov_b64 v[34:35], 0
	v_mov_b64 v[36:37], 0
	v_mov_b64 v[38:39], 0
	v_mov_b64 v[40:41], 0
	v_mov_b64 v[42:43], 0
	v_mov_b64 v[44:45], 0
	v_mov_b64 v[46:47], 0
	v_mov_b64 v[48:49], 0
	v_mov_b64 v[50:51], 0
	v_mov_b64 v[52:53], 0
	v_mov_b64 v[54:55], 0
	v_mov_b64 v[56:57], 0
	v_mov_b64 v[58:59], 0
	v_mov_b64 v[60:61], 0
	v_mov_b64 v[62:63], 0
	v_mov_b64 v[64:65], 0
	v_mov_b64 v[66:67], 0
	v_mov_b64 v[68:69], 0
	v_mov_b64 v[70:71], 0
	v_mov_b64 v[72:73], 0
	v_mov_b64 v[74:75], 0
	v_mov_b64 v[76:77], 0
	v_mov_b64 v[78:79], 0
	v_mov_b64 v[80:81], 0
	v_mov_b64 v[82:83], 0
	v_mov_b64 v[84:85], 0
	v_mov_b64 v[86:87], 0
	v_mov_b64 v[88:89], 0
	v_mov_b64 v[90:91], 0
	v_mov_b64 v[92:93], 0
	v_mov_b64 v[94:95], 0
	v_mov_b64 v[96:97], 0
	v_mov_b64 v[98:99], 0
	v_mov_b64 v[100:101], 0
	v_mov_b64 v[102:103], 0
	v_mov_b64 v[104:105], 0
	v_mov_b64 v[106:107], 0
	v_mov_b64 v[108:109], 0
	v_mov_b64 v[110:111], 0
	v_mov_b64 v[112:113], 0
	v_mov_b64 v[114:115], 0
	v_mov_b64 v[116:117], 0
	v_mov_b64 v[118:119], 0
	v_mov_b64 v[120:121], 0
	v_mov_b64 v[122:123], 0
	v_mov_b64 v[124:125], 0
	v_mov_b64 v[126:127], 0
	s_mov_b32 s91, s83
	s_and_saveexec_b64 s[22:23], s[6:7]
	s_cbranch_execz .LBB0_134
	s_barrier
.LBB0_134:
	s_or_b64 exec, exec, s[22:23]
	s_add_u32 s22, s38, s86
	s_addc_u32 s23, s39, 0
	s_add_u32 s42, s14, s86
	s_addc_u32 s43, s15, 0
	s_add_u32 s46, s14, s34
	s_addc_u32 s47, s15, 0
	s_add_u32 s68, s38, s34
	s_addc_u32 s69, s39, 0
	s_add_u32 s70, s14, s18
	s_waitcnt vmcnt(63)
	s_addc_u32 s71, s15, 0
	s_add_u32 s76, s38, s18
	s_addc_u32 s77, s39, 0
	s_mov_b32 s81, 0
	s_mov_b64 s[78:79], s[38:39]
	s_mov_b64 vcc, s[14:15]
	s_barrier
	s_barrier

.LBB0_1534:
	v_readlane_b32 s10, v255, 20
	v_readlane_b32 s11, v255, 21
	s_lshl_b64 s[2:3], s[10:11], 23
	s_add_u32 s19, s26, s2
	s_addc_u32 s37, s27, s3
	s_add_u32 s2, s26, 0x3c00000
	s_addc_u32 s3, s27, 0
	s_lshl_b32 s10, s10, 12
	s_ashr_i32 s11, s10, 31
	s_lshl_b64 s[10:11], s[10:11], 2
	s_waitcnt lgkmcnt(0)
	s_add_u32 s12, s6, s10
	s_addc_u32 s13, s7, s11
	s_add_i32 s6, s8, s9
	s_ashr_i32 s7, s6, 31
	s_lshr_b32 s7, s7, 25
	s_add_i32 s7, s6, s7
	s_and_b32 s8, s7, 0xff80
	s_sub_i32 s6, s6, s8
	s_bfe_i32 s8, s6, 0x80000
	s_bfe_u32 s8, s8, 0x3000c
	s_add_i32 s8, s6, s8
	s_bfe_i32 s9, s8, 0x80000
	s_and_b32 s8, s8, 0xf8
	s_sub_i32 s6, s6, s8
	s_sext_i32_i8 s6, s6
	s_lshl_b32 s7, s7, 4
	s_sext_i32_i16 s9, s9
	s_and_b32 s7, s7, 0xfffff800
	s_lshl_b32 s6, s6, 8
	v_ashrrev_i32_e32 v1, 6, v0
	v_lshlrev_b32_e32 v2, 4, v0
	v_lshrrev_b32_e32 v3, 31, v0
	s_add_i32 s38, s6, s7
	s_lshl_b32 s6, s9, 5
	v_add_u32_e32 v3, v1, v3
	v_and_b32_e32 v10, 48, v2
	v_lshlrev_b32_e32 v2, 9, v0
	s_and_b32 s40, s6, 0xffffff00
	v_ashrrev_i32_e32 v9, 1, v3
	v_and_b32_e32 v3, 0x3fffffe, v3
	v_and_b32_e32 v11, 0x7800, v2
	s_ashr_i32 s39, s38, 31
	s_ashr_i32 s41, s40, 31
	v_lshlrev_b32_e32 v135, 10, v1
	v_sub_u32_e32 v3, v1, v3
	v_lshl_or_b32 v2, v9, 15, v11
	s_lshl_b64 s[6:7], s[38:39], 11
	s_lshl_b64 s[8:9], s[40:41], 11
	v_and_b32_e32 v8, 32, v0
	v_lshl_add_u32 v2, v3, 6, v2
	s_add_u32 s14, s19, s8
	v_add_u32_e32 v137, 0x10000, v135
	v_bitop3_b32 v128, v2, v10, v8 bitop3:0xf6
	s_addc_u32 s15, s37, s9
	v_readfirstlane_b32 s8, v137
	v_add_u32_e32 v139, 0x12000, v135
	v_lshl_add_u64 v[2:3], s[14:15], 0, v[128:129]
	s_mov_b32 m0, s8
	s_mov_b64 s[10:11], 0x20000
	v_readfirstlane_b32 s8, v139
	s_add_u32 s22, s16, s6
	global_load_lds_dwordx4 v128, s[14:15]
	v_lshl_add_u64 v[4:5], v[2:3], 0, s[10:11]
	s_mov_b32 m0, s8
	s_addc_u32 s23, s17, s7
	v_readfirstlane_b32 s6, v135
	v_add_u32_e32 v141, 0x2000, v135
	global_load_lds_dwordx4 v[4:5], off
	v_lshl_add_u64 v[4:5], s[22:23], 0, v[128:129]
	s_mov_b32 m0, s6
	v_readfirstlane_b32 s6, v141
	v_add_u32_e32 v142, 0x14000, v135
	global_load_lds_dwordx4 v128, s[22:23]
	v_lshl_add_u64 v[6:7], v[4:5], 0, s[10:11]
	s_mov_b32 m0, s6
	s_mov_b64 s[8:9], 0x40000
	v_readfirstlane_b32 s6, v142
	v_add_u32_e32 v143, 0x16000, v135
	global_load_lds_dwordx4 v[6:7], off
	v_lshl_add_u64 v[6:7], v[2:3], 0, s[8:9]
	s_mov_b32 m0, s6
	s_mov_b64 s[10:11], 0x60000
	v_readfirstlane_b32 s6, v143
	v_add_u32_e32 v144, 0x4000, v135
	global_load_lds_dwordx4 v[6:7], off
	v_lshl_add_u64 v[6:7], v[2:3], 0, s[10:11]
	s_mov_b32 m0, s6
	v_readfirstlane_b32 s6, v144
	v_add_u32_e32 v145, 0x6000, v135
	global_load_lds_dwordx4 v[6:7], off
	v_lshl_add_u64 v[6:7], v[4:5], 0, s[8:9]
	s_mov_b32 m0, s6
	v_readfirstlane_b32 s6, v145
	v_add_u32_e32 v146, 0x18000, v135
	global_load_lds_dwordx4 v[6:7], off
	v_lshl_add_u64 v[6:7], v[4:5], 0, s[10:11]
	s_mov_b32 m0, s6
	v_readfirstlane_b32 s6, v146
	v_add_u32_e32 v147, 0x1a000, v135
	global_load_lds_dwordx4 v[6:7], off
	v_lshl_add_u64 v[6:7], v[2:3], 0, s[44:45]
	s_mov_b32 m0, s6
	s_mov_b64 s[8:9], 0x20080
	v_readfirstlane_b32 s6, v147
	v_add_u32_e32 v148, 0x8000, v135
	global_load_lds_dwordx4 v[6:7], off
	v_lshl_add_u64 v[6:7], v[2:3], 0, s[8:9]
	s_mov_b32 m0, s6
	v_readfirstlane_b32 s6, v148
	v_add_u32_e32 v149, 0xa000, v135
	global_load_lds_dwordx4 v[6:7], off
	v_lshl_add_u64 v[6:7], v[4:5], 0, s[44:45]
	s_mov_b32 m0, s6
	v_readfirstlane_b32 s6, v149
	v_add_u32_e32 v150, 0x1c000, v135
	global_load_lds_dwordx4 v[6:7], off
	v_lshl_add_u64 v[4:5], v[4:5], 0, s[8:9]
	s_mov_b32 m0, s6
	v_readfirstlane_b32 s6, v150
	v_add_u32_e32 v151, 0x1e000, v135
	global_load_lds_dwordx4 v[4:5], off
	v_lshl_add_u64 v[4:5], v[2:3], 0, s[48:49]
	s_mov_b32 m0, s6
	v_readfirstlane_b32 s6, v151
	global_load_lds_dwordx4 v[4:5], off
	v_lshl_add_u64 v[2:3], v[2:3], 0, s[50:51]
	s_mov_b32 m0, s6
	v_and_b32_e32 v5, 48, v0
	global_load_lds_dwordx4 v[2:3], off
	v_and_b32_e32 v3, 15, v0
	v_lshlrev_b32_e32 v6, 6, v3
	v_lshlrev_b32_e32 v12, 2, v0
	v_or_b32_e32 v7, v6, v5
	v_and_b32_e32 v12, 32, v12
	s_mov_b32 s8, 0x10000
	v_and_b32_e32 v1, 3, v1
	v_bitop3_b32 v13, v7, s8, v12 bitop3:0xde
	s_mov_b32 s8, 0x14000
	v_ashrrev_i32_e32 v2, 8, v0
	v_lshlrev_b32_e32 v4, 12, v1
	v_bitop3_b32 v15, v7, s8, v12 bitop3:0xde
	s_mov_b32 s8, 0x18000
	v_lshlrev_b32_e32 v1, 5, v1
	v_cmp_eq_u32_e64 s[6:7], 1, v2
	v_lshlrev_b32_e32 v14, 6, v2
	v_bitop3_b32 v16, v7, s8, v12 bitop3:0xde
	s_mov_b32 s8, 0x1c000
	v_or_b32_e32 v152, v1, v3
	v_and_or_b32 v154, v0, 14, v1
	v_lshlrev_b32_e32 v1, 13, v2
	v_lshlrev_b32_e32 v2, 6, v0
	s_movk_i32 s18, 0x7f80
	v_bitop3_b32 v7, v7, s8, v12 bitop3:0xde
	s_movk_i32 s8, 0x100
	v_lshrrev_b32_e32 v18, 2, v0
	v_and_b32_e32 v2, 0x3c0, v2
	v_mul_lo_u32 v9, v9, s18
	v_bitop3_b32 v6, v6, v12, v5 bitop3:0x36
	v_cmp_gt_u32_e64 s[8:9], s8, v0
	v_and_b32_e32 v17, 1, v0
	v_and_b32_e32 v18, 12, v18
	v_bitop3_b32 v2, v2, v12, v5 bitop3:0x36
	v_or_b32_e32 v3, 0x800, v1
	v_or_b32_e32 v5, 0x1000, v1
	v_or_b32_e32 v12, 0x1800, v1
	v_bitop3_b32 v8, v10, v9, v8 bitop3:0xde
	v_and_b32_e32 v0, 0xffffffc0, v0
	v_or3_b32 v153, v14, v18, v17
	v_cmp_eq_u32_e64 s[10:11], 0, v17
	v_add3_u32 v132, v8, v11, v0
	v_mov_b32_e32 v133, v129
	v_add_u32_e32 v155, v13, v4
	v_add_u32_e32 v156, v6, v1
	v_add_u32_e32 v157, v2, v3
	v_add_u32_e32 v158, v2, v5
	v_add_u32_e32 v159, v2, v12
	v_add_u32_e32 v160, v15, v4
	v_add_u32_e32 v161, v16, v4
	v_add_u32_e32 v162, v7, v4
	s_waitcnt vmcnt(0)
	s_branch .LBB0_1537

.LBB0_1537:
	v_mov_b64 v[0:1], 0
	v_mov_b64 v[2:3], 0
	v_mov_b64 v[4:5], 0
	v_mov_b64 v[6:7], 0
	v_mov_b64 v[8:9], 0
	v_mov_b64 v[10:11], 0
	v_mov_b64 v[12:13], 0
	v_mov_b64 v[14:15], 0
	v_mov_b64 v[16:17], 0
	v_mov_b64 v[18:19], 0
	v_mov_b64 v[20:21], 0
	v_mov_b64 v[22:23], 0
	v_mov_b64 v[24:25], 0
	v_mov_b64 v[26:27], 0
	v_mov_b64 v[28:29], 0
	v_mov_b64 v[30:31], 0
	v_mov_b64 v[32:33], 0
	v_mov_b64 v[34:35], 0
	v_mov_b64 v[36:37], 0
	v_mov_b64 v[38:39], 0
	v_mov_b64 v[40:41], 0
	v_mov_b64 v[42:43], 0
	v_mov_b64 v[44:45], 0
	v_mov_b64 v[46:47], 0
	v_mov_b64 v[48:49], 0
	v_mov_b64 v[50:51], 0
	v_mov_b64 v[52:53], 0
	v_mov_b64 v[54:55], 0
	v_mov_b64 v[56:57], 0
	v_mov_b64 v[58:59], 0
	v_mov_b64 v[60:61], 0
	v_mov_b64 v[62:63], 0
	v_mov_b64 v[64:65], 0
	v_mov_b64 v[66:67], 0
	v_mov_b64 v[68:69], 0
	v_mov_b64 v[70:71], 0
	v_mov_b64 v[72:73], 0
	v_mov_b64 v[74:75], 0
	v_mov_b64 v[76:77], 0
	v_mov_b64 v[78:79], 0
	v_mov_b64 v[80:81], 0
	v_mov_b64 v[82:83], 0
	v_mov_b64 v[84:85], 0
	v_mov_b64 v[86:87], 0
	v_mov_b64 v[88:89], 0
	v_mov_b64 v[90:91], 0
	v_mov_b64 v[92:93], 0
	v_mov_b64 v[94:95], 0
	v_mov_b64 v[96:97], 0
	v_mov_b64 v[98:99], 0
	v_mov_b64 v[100:101], 0
	v_mov_b64 v[102:103], 0
	v_mov_b64 v[104:105], 0
	v_mov_b64 v[106:107], 0
	v_mov_b64 v[108:109], 0
	v_mov_b64 v[110:111], 0
	v_mov_b64 v[112:113], 0
	v_mov_b64 v[114:115], 0
	v_mov_b64 v[116:117], 0
	v_mov_b64 v[118:119], 0
	v_mov_b64 v[120:121], 0
	v_mov_b64 v[122:123], 0
	v_mov_b64 v[124:125], 0
	v_mov_b64 v[126:127], 0
	s_and_saveexec_b64 s[24:25], s[6:7]
	s_cbranch_execz .LBB0_1539
	s_barrier
.LBB0_1539:
	s_or_b64 exec, exec, s[24:25]
	s_waitcnt vmcnt(63)
	s_mov_b32 s18, -2
	s_mov_b64 s[24:25], s[22:23]
	s_mov_b64 s[42:43], s[14:15]
	s_barrier
	s_barrier

.LBB0_1555:
	v_readlane_b32 s2, v255, 20
	v_readlane_b32 s3, v255, 21
	s_add_i32 s34, s2, -2
	s_lshl_b64 s[2:3], s[34:35], 22
	s_add_u32 s2, s26, s2
	s_addc_u32 s3, s27, s3
	s_add_u32 s34, s2, 0x2100000
	s_addc_u32 s46, s3, 0
	s_add_u32 s2, s26, 0x3c00000
	s_addc_u32 s3, s27, 0
	s_add_u32 s12, s26, 0x7c00000
	s_addc_u32 s13, s27, 0
	s_add_i32 s6, s6, s7
	s_ashr_i32 s7, s6, 31
	s_lshr_b32 s7, s7, 26
	s_add_i32 s7, s6, s7
	s_and_b32 s8, s7, 0xffc0
	s_sub_i32 s6, s6, s8
	s_bfe_i32 s8, s6, 0x80000
	s_bfe_u32 s8, s8, 0x3000c
	s_add_i32 s8, s6, s8
	s_bfe_i32 s9, s8, 0x80000
	s_and_b32 s8, s8, 0xf8
	s_sub_i32 s6, s6, s8
	s_sext_i32_i8 s6, s6
	s_lshl_b32 s7, s7, 5
	s_sext_i32_i16 s9, s9
	s_and_b32 s7, s7, 0xfffff800
	s_lshl_b32 s6, s6, 8
	v_ashrrev_i32_e32 v1, 6, v0
	v_lshlrev_b32_e32 v2, 4, v0
	v_lshrrev_b32_e32 v3, 31, v0
	s_add_i32 s40, s6, s7
	s_lshl_b32 s6, s9, 5
	v_add_u32_e32 v3, v1, v3
	v_and_b32_e32 v10, 48, v2
	v_lshlrev_b32_e32 v2, 9, v0
	s_and_b32 s42, s6, 0xffffff00
	v_ashrrev_i32_e32 v9, 1, v3
	v_and_b32_e32 v3, 0x3fffffe, v3
	v_and_b32_e32 v11, 0x7800, v2
	s_ashr_i32 s41, s40, 31
	s_ashr_i32 s43, s42, 31
	v_lshlrev_b32_e32 v134, 10, v1
	v_sub_u32_e32 v3, v1, v3
	v_lshl_or_b32 v2, v9, 15, v11
	s_lshl_b64 s[6:7], s[40:41], 11
	s_lshl_b64 s[8:9], s[42:43], 11
	v_and_b32_e32 v8, 32, v0
	v_lshl_add_u32 v2, v3, 6, v2
	s_waitcnt lgkmcnt(0)
	s_add_u32 s14, s34, s8
	v_add_u32_e32 v135, 0x10000, v134
	v_bitop3_b32 v128, v2, v10, v8 bitop3:0xf6
	s_addc_u32 s15, s46, s9
	v_readfirstlane_b32 s8, v135
	v_add_u32_e32 v136, 0x12000, v134
	v_lshl_add_u64 v[2:3], s[14:15], 0, v[128:129]
	s_mov_b32 m0, s8
	s_mov_b64 s[10:11], 0x20000
	v_readfirstlane_b32 s8, v136
	s_add_u32 s18, s16, s6
	global_load_lds_dwordx4 v128, s[14:15]
	v_lshl_add_u64 v[4:5], v[2:3], 0, s[10:11]
	s_mov_b32 m0, s8
	s_addc_u32 s19, s17, s7
	v_readfirstlane_b32 s6, v134
	v_add_u32_e32 v137, 0x2000, v134
	global_load_lds_dwordx4 v[4:5], off
	v_lshl_add_u64 v[4:5], s[18:19], 0, v[128:129]
	s_mov_b32 m0, s6
	v_readfirstlane_b32 s6, v137
	v_add_u32_e32 v138, 0x14000, v134
	global_load_lds_dwordx4 v128, s[18:19]
	v_lshl_add_u64 v[6:7], v[4:5], 0, s[10:11]
	s_mov_b32 m0, s6
	s_mov_b64 s[8:9], 0x40000
	v_readfirstlane_b32 s6, v138
	v_add_u32_e32 v139, 0x16000, v134
	global_load_lds_dwordx4 v[6:7], off
	v_lshl_add_u64 v[6:7], v[2:3], 0, s[8:9]
	s_mov_b32 m0, s6
	s_mov_b64 s[10:11], 0x60000
	v_readfirstlane_b32 s6, v139
	v_add_u32_e32 v140, 0x4000, v134
	global_load_lds_dwordx4 v[6:7], off
	v_lshl_add_u64 v[6:7], v[2:3], 0, s[10:11]
	s_mov_b32 m0, s6
	v_readfirstlane_b32 s6, v140
	v_add_u32_e32 v141, 0x6000, v134
	global_load_lds_dwordx4 v[6:7], off
	v_lshl_add_u64 v[6:7], v[4:5], 0, s[8:9]
	s_mov_b32 m0, s6
	v_readfirstlane_b32 s6, v141
	v_add_u32_e32 v142, 0x18000, v134
	global_load_lds_dwordx4 v[6:7], off
	v_lshl_add_u64 v[6:7], v[4:5], 0, s[10:11]
	s_mov_b32 m0, s6
	v_readfirstlane_b32 s6, v142
	v_add_u32_e32 v143, 0x1a000, v134
	global_load_lds_dwordx4 v[6:7], off
	v_lshl_add_u64 v[6:7], v[2:3], 0, s[44:45]
	s_mov_b32 m0, s6
	s_mov_b64 s[8:9], 0x20080
	v_readfirstlane_b32 s6, v143
	v_add_u32_e32 v144, 0x8000, v134
	global_load_lds_dwordx4 v[6:7], off
	v_lshl_add_u64 v[6:7], v[2:3], 0, s[8:9]
	s_mov_b32 m0, s6
	v_readfirstlane_b32 s6, v144
	v_add_u32_e32 v145, 0xa000, v134
	global_load_lds_dwordx4 v[6:7], off
	v_lshl_add_u64 v[6:7], v[4:5], 0, s[44:45]
	s_mov_b32 m0, s6
	v_readfirstlane_b32 s6, v145
	v_add_u32_e32 v146, 0x1c000, v134
	global_load_lds_dwordx4 v[6:7], off
	v_lshl_add_u64 v[4:5], v[4:5], 0, s[8:9]
	s_mov_b32 m0, s6
	v_readfirstlane_b32 s6, v146
	v_add_u32_e32 v147, 0x1e000, v134
	global_load_lds_dwordx4 v[4:5], off
	v_lshl_add_u64 v[4:5], v[2:3], 0, s[48:49]
	s_mov_b32 m0, s6
	v_readfirstlane_b32 s6, v147
	global_load_lds_dwordx4 v[4:5], off
	v_lshl_add_u64 v[2:3], v[2:3], 0, s[50:51]
	s_mov_b32 m0, s6
	v_and_b32_e32 v5, 48, v0
	global_load_lds_dwordx4 v[2:3], off
	v_and_b32_e32 v3, 15, v0
	v_lshlrev_b32_e32 v3, 6, v3
	v_lshlrev_b32_e32 v7, 2, v0
	v_ashrrev_i32_e32 v2, 8, v0
	v_or_b32_e32 v6, v3, v5
	v_and_b32_e32 v7, 32, v7
	s_mov_b32 s8, 0x10000
	v_lshrrev_b32_e32 v17, 2, v0
	v_bitop3_b32 v12, v6, s8, v7 bitop3:0xde
	v_lshlrev_b32_e32 v13, 6, v2
	s_mov_b32 s8, 0x14000
	v_and_b32_e32 v16, 1, v0
	v_and_b32_e32 v17, 12, v17
	v_and_b32_e32 v1, 3, v1
	v_bitop3_b32 v14, v6, s8, v7 bitop3:0xde
	s_mov_b32 s8, 0x18000
	v_or3_b32 v148, v13, v17, v16
	v_and_b32_e32 v13, 14, v0
	v_cmp_eq_u32_e64 s[6:7], 1, v2
	v_lshlrev_b32_e32 v4, 12, v1
	v_bitop3_b32 v15, v6, s8, v7 bitop3:0xde
	s_mov_b32 s8, 0x1c000
	v_lshl_or_b32 v149, v1, 5, v13
	v_lshlrev_b32_e32 v1, 13, v2
	v_lshlrev_b32_e32 v2, 6, v0
	s_movk_i32 s22, 0x7f80
	v_bitop3_b32 v6, v6, s8, v7 bitop3:0xde
	s_movk_i32 s8, 0x100
	v_and_b32_e32 v2, 0x3c0, v2
	v_mul_lo_u32 v9, v9, s22
	v_bitop3_b32 v3, v3, v7, v5 bitop3:0x36
	v_cmp_gt_u32_e64 s[8:9], s8, v0
	v_bitop3_b32 v2, v2, v7, v5 bitop3:0x36
	v_or_b32_e32 v5, 0x800, v1
	v_or_b32_e32 v7, 0x1000, v1
	v_or_b32_e32 v13, 0x1800, v1
	v_bitop3_b32 v8, v10, v9, v8 bitop3:0xde
	v_and_b32_e32 v0, 0xffffffc0, v0
	v_cmp_eq_u32_e64 s[10:11], 0, v16
	v_add3_u32 v132, v8, v11, v0
	v_mov_b32_e32 v133, v129
	v_add_u32_e32 v150, v12, v4
	v_add_u32_e32 v151, v3, v1
	v_add_u32_e32 v152, v2, v5
	v_add_u32_e32 v153, v2, v7
	v_add_u32_e32 v154, v2, v13
	v_add_u32_e32 v155, v14, v4
	v_add_u32_e32 v156, v15, v4
	v_add_u32_e32 v157, v6, v4
	s_waitcnt vmcnt(0)
	s_branch .LBB0_1557

.LBB0_1559:
	s_or_b64 exec, exec, s[22:23]
	s_waitcnt vmcnt(63)
	s_mov_b32 s38, -2
	s_mov_b64 s[22:23], s[18:19]
	s_mov_b64 s[24:25], s[14:15]
	s_barrier
	s_barrier
